# PAIR epilogue inputs (ssq partials, bias) and ROPE cos/sin table staged to LDS by LDS-DMA at unit start; unit-start vmcnt(0) dropped in both; FINAL loop loads issued together
# speedup vs baseline: 1.0057x; 1.0057x over previous
.LBB0_20:
	v_ashrrev_i32_e32 v2, 7, v4
	v_ashrrev_i32_e32 v3, 31, v2
	v_lshlrev_b64 v[6:7], 6, v[2:3]
	v_lshl_add_u64 v[18:19], s[76:77], 0, v[6:7]
	global_load_dwordx4 v[6:9], v[18:19], off offset:48
	global_load_dwordx4 v[10:13], v[18:19], off offset:32
	global_load_dwordx4 v[14:17], v[18:19], off offset:16
	s_nop 0
	global_load_dwordx4 v[18:21], v[18:19], off
	v_ashrrev_i32_e32 v24, 15, v4
	v_ashrrev_i32_e32 v25, 31, v24
	v_lshlrev_b64 v[24:25], 19, v[24:25]
	v_lshlrev_b32_e32 v26, 9, v1
	v_lshl_add_u64 v[24:25], s[74:75], 0, v[24:25]
	v_and_b32_e32 v190, 0x78000, v26
	v_and_b32_e32 v27, 56, v1
	v_lshl_add_u64 v[24:25], v[24:25], 0, v[190:191]
	v_and_b32_e32 v190, 0x7f80, v4
	v_lshl_add_u64 v[24:25], v[24:25], 0, v[190:191]
	v_lshlrev_b32_e32 v190, 1, v27
	v_lshl_add_u64 v[24:25], v[24:25], 0, v[190:191]
	global_load_dwordx4 v[26:29], v[24:25], off
	v_and_b32_e32 v190, 0x3f8, v1
	v_lshlrev_b32_e32 v190, 2, v190
	global_load_dwordx4 v[30:33], v190, s[4:5] offset:16
	global_load_dwordx4 v[34:37], v190, s[4:5]
	s_mov_b32 s0, 0xf800000
	v_lshlrev_b64 v[2:3], 12, v[2:3]
	v_lshl_add_u64 v[2:3], s[38:39], 0, v[2:3]
	s_waitcnt vmcnt(5)
	v_add_f32_e32 v10, v10, v11
	v_add_f32_e32 v12, v12, v13
	s_waitcnt vmcnt(3)
	v_mov_b32_e32 v22, v19
	v_mov_b32_e32 v23, v20
	v_mov_b32_e32 v19, v21
	v_mov_b32_e32 v20, v15
	v_mov_b32_e32 v21, v16
	v_mov_b32_e32 v15, v17
	v_pk_add_f32 v[18:19], v[22:23], v[18:19]
	v_pk_add_f32 v[14:15], v[20:21], v[14:15]
	v_add_f32_e32 v5, v18, v19
	v_pk_add_f32 v[14:15], v[14:15], v[14:15] op_sel:[0,1] op_sel_hi:[1,0]
	v_add_f32_e32 v18, 0, v5
	v_mov_b32_e32 v19, v6
	v_mov_b32_e32 v15, v7
	v_mov_b32_e32 v11, v8
	v_mov_b32_e32 v13, v9
	v_pk_add_f32 v[6:7], v[18:19], v[14:15]
	v_pk_add_f32 v[8:9], v[10:11], v[12:13]
	v_and_b32_e32 v10, 0x3f8, v1
	v_pk_add_f32 v[6:7], v[6:7], v[8:9]
	s_nop 0
	v_add_f32_e32 v5, v6, v7
	v_fmamk_f32 v5, v5, 0x3a800000, v224
	v_cmp_gt_f32_e32 vcc, s0, v5
	v_mul_f32_e32 v6, 0x4f800000, v5
	s_nop 0
	v_cndmask_b32_e32 v5, v5, v6, vcc
	v_sqrt_f32_e32 v6, v5
	s_nop 0
	v_add_u32_e32 v7, -1, v6
	v_fma_f32 v8, -v7, v6, v5
	v_cmp_ge_f32_e64 s[0:1], 0, v8
	v_add_u32_e32 v8, 1, v6
	s_nop 0
	v_cndmask_b32_e64 v7, v6, v7, s[0:1]
	v_fma_f32 v6, -v8, v6, v5
	v_cmp_lt_f32_e64 s[0:1], 0, v6
	s_nop 1
	v_cndmask_b32_e64 v6, v7, v8, s[0:1]
	v_mul_f32_e32 v7, 0x37800000, v6
	v_cndmask_b32_e32 v6, v6, v7, vcc
	v_mov_b32_e32 v7, 0x260
	v_cmp_class_f32_e32 vcc, v5, v7
	s_nop 1
	v_cndmask_b32_e32 v5, v6, v5, vcc
	v_div_scale_f32 v6, s[0:1], v5, v5, 1.0
	v_rcp_f32_e32 v7, v6
	s_nop 0
	v_fma_f32 v8, -v6, v7, 1.0
	v_fmac_f32_e32 v7, v8, v7
	v_div_scale_f32 v8, vcc, 1.0, v5, 1.0
	v_mul_f32_e32 v9, v8, v7
	v_fma_f32 v11, -v6, v9, v8
	v_fmac_f32_e32 v9, v11, v7
	v_fma_f32 v6, -v6, v9, v8
	v_div_fmas_f32 v6, v6, v7, v9
	v_div_fixup_f32 v18, v6, v5, 1.0
	v_add_u32_e32 v4, s84, v4
	v_cmp_lt_i32_e32 vcc, s73, v4
	v_lshl_add_u64 v[2:3], v[2:3], 0, v[190:191]
	v_add_u32_e32 v1, s2, v1
	s_or_b64 s[8:9], vcc, s[8:9]
	s_waitcnt vmcnt(2)
	v_lshlrev_b32_e32 v20, 16, v26
	v_and_b32_e32 v21, 0xffff0000, v26
	v_lshlrev_b32_e32 v6, 16, v27
	v_and_b32_e32 v7, 0xffff0000, v27
	v_pk_mul_f32 v[6:7], v[18:19], v[6:7] op_sel_hi:[0,1]
	v_pk_mul_f32 v[20:21], v[18:19], v[20:21] op_sel_hi:[0,1]
	s_waitcnt vmcnt(0)
	v_pk_mul_f32 v[16:17], v[36:37], v[6:7]
	v_lshlrev_b32_e32 v6, 16, v28
	v_and_b32_e32 v7, 0xffff0000, v28
	v_lshlrev_b32_e32 v8, 16, v29
	v_and_b32_e32 v9, 0xffff0000, v29
	v_pk_mul_f32 v[14:15], v[34:35], v[20:21]
	v_pk_mul_f32 v[6:7], v[18:19], v[6:7] op_sel_hi:[0,1]
	v_pk_mul_f32 v[8:9], v[18:19], v[8:9] op_sel_hi:[0,1]
	v_pk_mul_f32 v[8:9], v[32:33], v[8:9]
	v_pk_mul_f32 v[6:7], v[30:31], v[6:7]
	global_store_dwordx4 v[2:3], v[14:17], off
	global_store_dwordx4 v[2:3], v[6:9], off offset:16
	s_andn2_b64 exec, exec, s[8:9]
	s_cbranch_execnz .LBB0_20

.LBB0_218:
	s_barrier
	s_lshl_b32 s6, s45, 1
	s_lshl_b32 s26, s8, 14
	v_lshlrev_b32_e32 v3, 4, v227
	s_add_u32 s26, s86, s26
	s_addc_u32 s27, s87, 0
	v_add_u32_e32 v2, s6, v3
	s_add_i32 m0, s6, 0x21000
	s_nop 0
	global_load_lds_dwordx4 v2, s[26:27]
	global_load_lds_dwordx4 v2, s[26:27] offset:1024
	s_add_i32 s85, s85, 1
	s_mul_i32 s6, s85, s70
	s_mul_hi_u32 s7, s85, s56
	s_add_i32 s7, s7, s6
	s_mul_i32 s6, s85, s56
	s_add_u32 s26, s6, s55
	s_addc_u32 s27, s7, s88
	v_mov_b64_e32 v[2:3], s[24:25]
	v_cmp_ge_i64_e32 vcc, s[26:27], v[2:3]
	v_cmp_lt_i64_e64 s[6:7], s[26:27], v[2:3]
	s_cbranch_vccnz .LBB0_220
	s_ashr_i32 s9, s26, 31
	s_lshr_b32 s9, s9, 29
	s_add_i32 s9, s26, s9
	s_ashr_i32 s16, s9, 3
	s_and_b32 s9, s9, -8
	s_sub_i32 s9, s26, s9
	s_lshr_b32 s17, s9, 31
	s_or_b32 s17, s89, s17
	s_mul_i32 s9, s17, s9
	s_add_i32 s9, s9, s16
	s_abs_i32 s17, s9
	s_mul_hi_u32 s18, s17, s66
	s_mul_i32 s19, s18, s2
	s_ashr_i32 s16, s9, 31
	s_sub_i32 s17, s17, s19
	s_xor_b32 s16, s16, s73
	s_add_i32 s19, s18, 1
	s_sub_i32 s26, s17, s2
	s_cmp_ge_u32 s17, s2
	s_cselect_b32 s18, s19, s18
	s_cselect_b32 s17, s26, s17
	s_add_i32 s19, s18, 1
	s_cmp_ge_u32 s17, s2
	s_cselect_b32 s17, s19, s18
	s_xor_b32 s17, s17, s16
	s_sub_i32 s16, s17, s16
	s_lshl_b32 s17, s16, 3
	s_sub_i32 s18, 0x80, s17
	s_min_i32 s18, s18, 8
	s_abs_i32 s19, s18
	v_cvt_f32_u32_e32 v2, s19
	s_sub_i32 s27, 0, s19
	s_mul_i32 s16, s16, s49
	s_sub_i32 s9, s9, s16
	v_rcp_iflag_f32_e32 v2, v2
	s_abs_i32 s26, s9
	s_xor_b32 s16, s9, s18
	s_ashr_i32 s16, s16, 31
	v_mul_f32_e32 v2, 0x4f7ffffe, v2
	v_cvt_u32_f32_e32 v2, v2
	s_nop 0
	v_readfirstlane_b32 s46, v2
	s_mul_i32 s27, s27, s46
	s_mul_hi_u32 s27, s46, s27
	s_add_i32 s46, s46, s27
	s_mul_hi_u32 s27, s26, s46
	s_mul_i32 s46, s27, s19
	s_sub_i32 s26, s26, s46
	s_add_i32 s46, s27, 1
	s_sub_i32 s47, s26, s19
	s_cmp_ge_u32 s26, s19
	s_cselect_b32 s27, s46, s27
	s_cselect_b32 s26, s47, s26
	s_add_i32 s46, s27, 1
	s_cmp_ge_u32 s26, s19
	s_cselect_b32 s19, s46, s27
	s_xor_b32 s19, s19, s16
	s_sub_i32 s16, s19, s16
	s_mul_i32 s18, s16, s18
	s_sub_i32 s9, s9, s18
	s_add_i32 s18, s9, s17
.LBB0_220:
	s_ashr_i32 s19, s18, 31
	s_lshl_b64 s[26:27], s[18:19], 19
	s_add_u32 s26, s53, s26
	s_addc_u32 s27, s52, s27
	s_and_b64 s[46:47], s[6:7], exec
	s_cselect_b32 s9, s27, s43
	s_cselect_b32 s19, s26, s42
	s_ashr_i32 s17, s16, 31
	s_lshl_b64 s[46:47], s[16:17], 19
	s_add_u32 s80, s91, s46
	s_addc_u32 s81, s93, s47
	s_and_b64 s[46:47], s[6:7], exec
	s_cselect_b32 s17, s81, s11
	s_cselect_b32 s54, s80, s10
	s_add_u32 s62, s10, 0x100
	s_addc_u32 s63, s11, 0
	s_add_u32 s10, s42, 0xc000
	v_mov_b32_e32 v2, 0
	s_addc_u32 s11, s43, 0
	s_mov_b32 s67, -2
	v_mov_b32_e32 v3, v2
	v_mov_b32_e32 v4, v2
	v_mov_b32_e32 v5, v2
	v_mov_b32_e32 v6, v2
	v_mov_b32_e32 v7, v2
	v_mov_b32_e32 v8, v2
	v_mov_b32_e32 v9, v2
	v_mov_b32_e32 v18, v2
	v_mov_b32_e32 v19, v2
	v_mov_b32_e32 v20, v2
	v_mov_b32_e32 v21, v2
	v_mov_b32_e32 v22, v2
	v_mov_b32_e32 v23, v2
	v_mov_b32_e32 v24, v2
	v_mov_b32_e32 v25, v2
	v_mov_b32_e32 v34, v2
	v_mov_b32_e32 v35, v2
	v_mov_b32_e32 v36, v2
	v_mov_b32_e32 v37, v2
	v_mov_b32_e32 v38, v2
	v_mov_b32_e32 v39, v2
	v_mov_b32_e32 v40, v2
	v_mov_b32_e32 v41, v2
	v_mov_b32_e32 v58, v2
	v_mov_b32_e32 v59, v2
	v_mov_b32_e32 v60, v2
	v_mov_b32_e32 v61, v2
	v_mov_b32_e32 v62, v2
	v_mov_b32_e32 v63, v2
	v_mov_b32_e32 v64, v2
	v_mov_b32_e32 v65, v2
	v_mov_b32_e32 v10, v2
	v_mov_b32_e32 v11, v2
	v_mov_b32_e32 v12, v2
	v_mov_b32_e32 v13, v2
	v_mov_b32_e32 v14, v2
	v_mov_b32_e32 v15, v2
	v_mov_b32_e32 v16, v2
	v_mov_b32_e32 v17, v2
	v_mov_b32_e32 v26, v2
	v_mov_b32_e32 v27, v2
	v_mov_b32_e32 v28, v2
	v_mov_b32_e32 v29, v2
	v_mov_b32_e32 v30, v2
	v_mov_b32_e32 v31, v2
	v_mov_b32_e32 v32, v2
	v_mov_b32_e32 v33, v2
	v_mov_b32_e32 v42, v2
	v_mov_b32_e32 v43, v2
	v_mov_b32_e32 v44, v2
	v_mov_b32_e32 v45, v2
	v_mov_b32_e32 v46, v2
	v_mov_b32_e32 v47, v2
	v_mov_b32_e32 v48, v2
	v_mov_b32_e32 v49, v2
	v_mov_b32_e32 v74, v2
	v_mov_b32_e32 v75, v2
	v_mov_b32_e32 v76, v2
	v_mov_b32_e32 v77, v2
	v_mov_b32_e32 v78, v2
	v_mov_b32_e32 v79, v2
	v_mov_b32_e32 v80, v2
	v_mov_b32_e32 v81, v2
	v_mov_b32_e32 v82, v2
	v_mov_b32_e32 v83, v2
	v_mov_b32_e32 v84, v2
	v_mov_b32_e32 v85, v2
	v_mov_b32_e32 v86, v2
	v_mov_b32_e32 v87, v2
	v_mov_b32_e32 v88, v2
	v_mov_b32_e32 v89, v2
	v_mov_b32_e32 v98, v2
	v_mov_b32_e32 v99, v2
	v_mov_b32_e32 v100, v2
	v_mov_b32_e32 v101, v2
	v_mov_b32_e32 v102, v2
	v_mov_b32_e32 v103, v2
	v_mov_b32_e32 v104, v2
	v_mov_b32_e32 v105, v2
	v_mov_b32_e32 v114, v2
	v_mov_b32_e32 v115, v2
	v_mov_b32_e32 v116, v2
	v_mov_b32_e32 v117, v2
	v_mov_b32_e32 v118, v2
	v_mov_b32_e32 v119, v2
	v_mov_b32_e32 v120, v2
	v_mov_b32_e32 v121, v2
	v_mov_b32_e32 v130, v2
	v_mov_b32_e32 v131, v2
	v_mov_b32_e32 v132, v2
	v_mov_b32_e32 v133, v2
	v_mov_b32_e32 v134, v2
	v_mov_b32_e32 v135, v2
	v_mov_b32_e32 v136, v2
	v_mov_b32_e32 v137, v2
	v_mov_b32_e32 v90, v2
	v_mov_b32_e32 v91, v2
	v_mov_b32_e32 v92, v2
	v_mov_b32_e32 v93, v2
	v_mov_b32_e32 v94, v2
	v_mov_b32_e32 v95, v2
	v_mov_b32_e32 v96, v2
	v_mov_b32_e32 v97, v2
	v_mov_b32_e32 v106, v2
	v_mov_b32_e32 v107, v2
	v_mov_b32_e32 v108, v2
	v_mov_b32_e32 v109, v2
	v_mov_b32_e32 v110, v2
	v_mov_b32_e32 v111, v2
	v_mov_b32_e32 v112, v2
	v_mov_b32_e32 v113, v2
	v_mov_b32_e32 v122, v2
	v_mov_b32_e32 v123, v2
	v_mov_b32_e32 v124, v2
	v_mov_b32_e32 v125, v2
	v_mov_b32_e32 v126, v2
	v_mov_b32_e32 v127, v2
	v_mov_b32_e32 v128, v2
	v_mov_b32_e32 v129, v2
	v_mov_b32_e32 v138, v2
	v_mov_b32_e32 v139, v2
	v_mov_b32_e32 v140, v2
	v_mov_b32_e32 v141, v2
	v_mov_b32_e32 v142, v2
	v_mov_b32_e32 v143, v2
	v_mov_b32_e32 v144, v2
	v_mov_b32_e32 v145, v2

.LBB0_224:
	s_lshl_b32 s50, s8, 8
	s_add_i32 s50, s50, s71
	v_or_b32_e32 v214, s50, v197
	v_ashrrev_i32_e32 v215, 31, v214
	v_or_b32_e32 v210, 16, v214
	v_or_b32_e32 v206, 32, v214
	v_lshlrev_b64 v[216:217], 6, v[214:215]
	v_ashrrev_i32_e32 v211, 31, v210
	v_ashrrev_i32_e32 v207, 31, v206
	v_or_b32_e32 v202, 48, v214
	v_add_u32_e32 v186, 0x80, v214
	v_lshl_add_u64 v[50:51], v[174:175], 0, v[216:217]
	v_lshlrev_b64 v[212:213], 6, v[210:211]
	v_lshlrev_b64 v[208:209], 6, v[206:207]
	v_ashrrev_i32_e32 v203, 31, v202
	v_ashrrev_i32_e32 v187, 31, v186
	v_lshl_add_u64 v[52:53], v[174:175], 0, v[212:213]
	global_load_dwordx4 v[218:221], v[50:51], off
	global_load_dwordx4 v[244:247], v[52:53], off
	v_lshl_add_u64 v[50:51], v[174:175], 0, v[208:209]
	v_lshlrev_b64 v[204:205], 6, v[202:203]
	v_lshlrev_b64 v[188:189], 6, v[186:187]
	v_add_u32_e32 v184, 0x90, v214
	v_lshl_add_u64 v[52:53], v[174:175], 0, v[204:205]
	global_load_dwordx4 v[248:251], v[50:51], off
	global_load_dwordx4 v[234:237], v[52:53], off
	v_lshl_add_u64 v[50:51], v[174:175], 0, v[188:189]
	v_ashrrev_i32_e32 v185, 31, v184
	global_load_dwordx4 v[158:161], v[50:51], off
	v_add_u32_e32 v182, 0xa0, v214
	v_lshlrev_b64 v[50:51], 6, v[184:185]
	v_lshl_add_u64 v[50:51], v[174:175], 0, v[50:51]
	v_ashrrev_i32_e32 v183, 31, v182
	v_add_u32_e32 v180, 0xb0, v214
	global_load_dwordx4 v[150:153], v[50:51], off
	v_lshlrev_b64 v[50:51], 6, v[182:183]
	v_lshl_add_u64 v[50:51], v[174:175], 0, v[50:51]
	v_ashrrev_i32_e32 v181, 31, v180
	global_load_dwordx4 v[146:149], v[50:51], off
	v_lshlrev_b64 v[50:51], 6, v[180:181]
	v_lshl_add_u64 v[50:51], v[174:175], 0, v[50:51]
	global_load_dwordx4 v[154:157], v[50:51], off
	s_ashr_i32 s8, s8, 5
	s_mul_hi_i32 s9, s8, s48
	s_mul_i32 s8, s8, s48
	s_lshl_b64 s[8:9], s[8:9], 2
	s_add_u32 s10, s36, s8
	s_addc_u32 s11, s37, s9
	s_lshl_b32 s8, s44, 8
	s_ashr_i32 s9, s8, 31
	s_lshl_b64 s[8:9], s[8:9], 2
	s_add_u32 s8, s10, s8
	s_addc_u32 s9, s11, s9
	global_load_dwordx4 v[66:69], v242, s[8:9] offset:16
	global_load_dwordx4 v[70:73], v242, s[8:9]
	global_load_dwordx4 v[50:53], v242, s[8:9] offset:528
	global_load_dwordx4 v[54:57], v242, s[8:9] offset:512
	v_and_b32_e32 v203, 64, v227
	v_xor_b32_e32 v187, 16, v227
	v_add_u32_e32 v203, 64, v203
	v_xor_b32_e32 v207, 32, v227
	v_cmp_lt_i32_e32 vcc, v187, v203
	s_cmp_lt_i32 s44, 6
	s_cselect_b64 s[10:11], -1, 0
	v_cndmask_b32_e32 v187, v227, v187, vcc
	v_cmp_lt_i32_e32 vcc, v207, v203
	v_lshlrev_b32_e32 v187, 2, v187
	s_and_b64 s[46:47], s[14:15], s[10:11]
	v_cndmask_b32_e32 v203, v227, v207, vcc
	v_lshlrev_b32_e32 v207, 2, v203
	s_and_b64 s[42:43], s[46:47], s[4:5]
	s_waitcnt vmcnt(0)
	v_add_f32_e32 v203, v218, v219
	v_add_f32_e32 v211, v220, v221
	v_add_f32_e32 v203, v203, v211
	v_add_f32_e32 v211, v244, v245
	v_add_f32_e32 v215, v246, v247
	v_add_f32_e32 v218, v248, v249
	v_add_f32_e32 v219, v250, v251
	v_add_f32_e32 v220, v234, v235
	v_add_f32_e32 v221, v236, v237
	v_add_f32_e32 v158, v158, v159
	v_add_f32_e32 v159, v160, v161
	v_add_f32_e32 v161, v211, v215
	v_add_f32_e32 v211, v218, v219
	v_add_f32_e32 v215, v220, v221
	v_add_f32_e32 v158, v158, v159
	v_add_f32_e32 v150, v150, v151
	v_add_f32_e32 v151, v152, v153
	v_add_f32_e32 v150, v150, v151
	ds_bpermute_b32 v160, v187, v203
	v_add_f32_e32 v146, v146, v147
	v_add_f32_e32 v147, v148, v149
	v_add_f32_e32 v146, v146, v147
	v_add_f32_e32 v148, v154, v155
	v_add_f32_e32 v149, v156, v157
	v_add_f32_e32 v148, v148, v149
	ds_bpermute_b32 v159, v187, v161
	ds_bpermute_b32 v220, v187, v211
	ds_bpermute_b32 v221, v187, v215
	ds_bpermute_b32 v222, v187, v158
	ds_bpermute_b32 v151, v187, v150
	ds_bpermute_b32 v147, v187, v146
	ds_bpermute_b32 v149, v187, v148
	s_waitcnt lgkmcnt(7)
	v_add_f32_e32 v218, v203, v160
	s_waitcnt lgkmcnt(6)
	v_add_f32_e32 v251, v161, v159
	s_waitcnt lgkmcnt(5)
	v_add_f32_e32 v249, v211, v220
	s_waitcnt lgkmcnt(4)
	v_add_f32_e32 v247, v215, v221
	s_waitcnt lgkmcnt(3)
	v_add_f32_e32 v245, v158, v222
	s_waitcnt lgkmcnt(2)
	v_add_f32_e32 v243, v150, v151
	s_waitcnt lgkmcnt(1)
	v_add_f32_e32 v211, v146, v147
	s_waitcnt lgkmcnt(0)
	v_add_f32_e32 v203, v148, v149
	ds_bpermute_b32 v219, v207, v218
	ds_bpermute_b32 v252, v207, v251
	ds_bpermute_b32 v250, v207, v249
	ds_bpermute_b32 v248, v207, v247
	ds_bpermute_b32 v246, v207, v245
	ds_bpermute_b32 v244, v207, v243
	ds_bpermute_b32 v215, v207, v211
	ds_bpermute_b32 v207, v207, v203
	v_mov_b32_e32 v158, 0
	v_mov_b32_e32 v150, 1.0
	v_mov_b32_e32 v151, 1.0
	v_mov_b32_e32 v152, 1.0
	v_mov_b32_e32 v153, 1.0
	v_mov_b32_e32 v146, 1.0
	v_mov_b32_e32 v147, 1.0
	v_mov_b32_e32 v148, 1.0
	v_mov_b32_e32 v149, 1.0
	v_mov_b32_e32 v159, 0
	v_mov_b32_e32 v160, 0
	v_mov_b32_e32 v161, 0
	v_mov_b32_e32 v156, 0
	v_mov_b32_e32 v157, 0
	v_mov_b32_e32 v154, 0
	v_mov_b32_e32 v155, 0
	s_and_saveexec_b64 s[8:9], s[42:43]
	s_cbranch_execz .LBB0_226
	v_and_b32_e32 v146, 0x3fc0, v216
	v_add_u32_e32 v146, 0x21000, v146
	ds_read_b128 v[154:157], v146 offset:32
	ds_read_b128 v[220:223], v146 offset:48
	ds_read_b128 v[150:153], v146
	s_nop 0
	ds_read_b128 v[146:149], v146 offset:16
	s_waitcnt lgkmcnt(3)
	v_pk_mul_f32 v[160:161], v[172:173], v[156:157]
	v_pk_mul_f32 v[158:159], v[170:171], v[154:155]
	s_waitcnt lgkmcnt(2)
	v_pk_mul_f32 v[154:155], v[172:173], v[222:223]
	v_pk_mul_f32 v[156:157], v[170:171], v[220:221]
.LBB0_226:
	s_or_b64 exec, exec, s[8:9]
	s_waitcnt lgkmcnt(7)
	v_add_f32_e32 v216, v218, v219
	v_fmamk_f32 v216, v216, 0x3a800000, v224
	v_rsq_f32_e32 v216, v216
	s_andn2_b64 vcc, exec, s[46:47]
	v_pk_fma_f32 v[218:219], v[138:139], v[216:217], v[66:67] op_sel_hi:[1,0,1]
	v_cndmask_b32_e64 v138, 0, 1, s[46:47]
	v_pk_fma_f32 v[220:221], v[144:145], v[216:217], v[72:73] op_sel_hi:[1,0,1]
	v_pk_fma_f32 v[222:223], v[142:143], v[216:217], v[70:71] op_sel_hi:[1,0,1]
	v_pk_fma_f32 v[144:145], v[140:141], v[216:217], v[68:69] op_sel_hi:[1,0,1]
	v_cmp_ne_u32_e64 s[8:9], 1, v138
	s_cbranch_vccnz .LBB0_228
	ds_bpermute_b32 v138, v187, v222
	ds_bpermute_b32 v139, v187, v223
	ds_bpermute_b32 v140, v187, v218
	ds_bpermute_b32 v142, v187, v220
	ds_bpermute_b32 v143, v187, v221
	ds_bpermute_b32 v141, v187, v219
	ds_bpermute_b32 v234, v187, v144
	ds_bpermute_b32 v235, v187, v145
	s_waitcnt lgkmcnt(6)
	v_pk_mul_f32 v[138:139], v[158:159], v[138:139]
	s_waitcnt lgkmcnt(3)
	v_pk_mul_f32 v[142:143], v[160:161], v[142:143]
	v_pk_fma_f32 v[222:223], v[222:223], v[150:151], v[138:139]
	s_waitcnt lgkmcnt(2)
	v_pk_mul_f32 v[138:139], v[156:157], v[140:141]
	s_waitcnt lgkmcnt(0)
	v_pk_mul_f32 v[140:141], v[154:155], v[234:235]
	v_pk_fma_f32 v[220:221], v[220:221], v[152:153], v[142:143]
	v_pk_fma_f32 v[144:145], v[144:145], v[148:149], v[140:141]
	v_pk_fma_f32 v[218:219], v[218:219], v[146:147], v[138:139]
.LBB0_228:
	s_and_b64 s[46:47], s[10:11], exec
	s_cselect_b32 s17, 0, -6
	s_cselect_b32 s47, s28, s83
	s_cselect_b32 s46, s61, s82
	s_add_i32 s17, s17, s44
	s_and_b32 s19, s17, -2
	v_and_b32_e32 v138, 0x1fcf, v214
	v_lshrrev_b32_e32 v138, s19, v138
	v_lshl_add_u64 v[140:141], s[46:47], 0, v[190:191]
	v_lshlrev_b32_e32 v138, 7, v138
	v_mov_b32_e32 v139, v191
	v_lshl_add_u64 v[142:143], v[140:141], 0, v[138:139]
	v_cndmask_b32_e64 v138, 1.0, v1, s[10:11]
	s_lshl_b32 s10, s17, 2
	s_or_b32 s46, s10, s72
	s_ashr_i32 s10, s50, 13
	s_mul_i32 s10, s10, 24
	s_lshl_b32 s44, -1, s19
	s_add_i32 s10, s46, s10
	v_bitop3_b32 v214, v214, s44, v229 bitop3:0x20
	v_pk_mul_f32 v[220:221], v[138:139], v[220:221] op_sel_hi:[0,1]
	v_pk_mul_f32 v[144:145], v[138:139], v[144:145] op_sel_hi:[0,1]
	s_lshl_b32 s47, s10, s19
	v_pk_mul_f32 v[222:223], v[138:139], v[222:223] op_sel_hi:[0,1]
	v_pk_mul_f32 v[234:235], v[138:139], v[218:219] op_sel_hi:[0,1]
	v_cvt_pk_bf16_f32 v218, v222, v223
	v_cvt_pk_bf16_f32 v219, v220, v221
	v_cvt_pk_bf16_f32 v220, v234, v235
	v_cvt_pk_bf16_f32 v221, v144, v145
	v_add_u32_e32 v144, s47, v214
	s_sub_i32 s17, 19, s19
	v_ashrrev_i32_e32 v145, 31, v144
	v_lshlrev_b64 v[144:145], s17, v[144:145]
	v_lshl_add_u64 v[144:145], v[144:145], 1, v[142:143]
	v_mov_b32_e32 v217, v216
	global_store_dwordx4 v[144:145], v[218:221], off
	v_mov_b32_e32 v144, v216
	v_mov_b32_e32 v145, v216
	v_pk_fma_f32 v[136:137], v[136:137], v[144:145], v[56:57]
	v_pk_fma_f32 v[134:135], v[134:135], v[216:217], v[54:55]
	v_pk_fma_f32 v[132:133], v[132:133], v[144:145], v[52:53]
	s_and_b64 vcc, exec, s[8:9]
	v_pk_fma_f32 v[130:131], v[130:131], v[216:217], v[50:51]
	s_cbranch_vccnz .LBB0_230
	ds_bpermute_b32 v144, v187, v134
	ds_bpermute_b32 v145, v187, v135
	ds_bpermute_b32 v216, v187, v130
	ds_bpermute_b32 v218, v187, v136
	ds_bpermute_b32 v219, v187, v137
	ds_bpermute_b32 v217, v187, v131
	ds_bpermute_b32 v220, v187, v132
	ds_bpermute_b32 v221, v187, v133
	s_waitcnt lgkmcnt(6)
	v_pk_mul_f32 v[144:145], v[158:159], v[144:145]
	s_waitcnt lgkmcnt(3)
	v_pk_mul_f32 v[158:159], v[160:161], v[218:219]
	v_pk_fma_f32 v[134:135], v[134:135], v[150:151], v[144:145]
	s_waitcnt lgkmcnt(2)
	v_pk_mul_f32 v[144:145], v[156:157], v[216:217]
	s_waitcnt lgkmcnt(0)
	v_pk_mul_f32 v[150:151], v[154:155], v[220:221]
	v_pk_fma_f32 v[136:137], v[136:137], v[152:153], v[158:159]
	v_pk_fma_f32 v[132:133], v[132:133], v[148:149], v[150:151]
	v_pk_fma_f32 v[130:131], v[130:131], v[146:147], v[144:145]
.LBB0_230:
	v_mov_b32_e32 v139, v138
	s_or_b32 s10, s10, 2
	v_mov_b32_e32 v144, v138
	v_mov_b32_e32 v145, v138
	v_pk_mul_f32 v[134:135], v[138:139], v[134:135]
	s_lshl_b32 s50, s10, s19
	v_pk_mul_f32 v[136:137], v[144:145], v[136:137]
	v_pk_mul_f32 v[144:145], v[144:145], v[132:133]
	v_pk_mul_f32 v[132:133], v[138:139], v[130:131]
	v_cvt_pk_bf16_f32 v130, v134, v135
	v_add_u32_e32 v134, s50, v214
	v_ashrrev_i32_e32 v135, 31, v134
	v_lshlrev_b64 v[134:135], s17, v[134:135]
	v_cvt_pk_bf16_f32 v131, v136, v137
	v_cvt_pk_bf16_f32 v132, v132, v133
	v_cvt_pk_bf16_f32 v133, v144, v145
	v_lshl_add_u64 v[134:135], v[134:135], 1, v[142:143]
	global_store_dwordx4 v[134:135], v[130:133], off
	v_mov_b32_e32 v146, 0
	v_mov_b32_e32 v134, 1.0
	v_mov_b32_e32 v135, 1.0
	v_mov_b32_e32 v136, 1.0
	v_mov_b32_e32 v137, 1.0
	v_mov_b32_e32 v130, 1.0
	v_mov_b32_e32 v131, 1.0
	v_mov_b32_e32 v132, 1.0
	v_mov_b32_e32 v133, 1.0
	v_mov_b32_e32 v147, 0
	v_mov_b32_e32 v148, 0
	v_mov_b32_e32 v149, 0
	v_mov_b32_e32 v144, 0
	v_mov_b32_e32 v145, 0
	v_mov_b32_e32 v142, 0
	v_mov_b32_e32 v143, 0
	s_and_saveexec_b64 s[10:11], s[42:43]
	s_cbranch_execz .LBB0_232
	v_and_b32_e32 v130, 0x3fc0, v212
	v_add_u32_e32 v130, 0x21000, v130
	ds_read_b128 v[142:145], v130 offset:32
	ds_read_b128 v[150:153], v130 offset:48
	ds_read_b128 v[134:137], v130
	s_nop 0
	ds_read_b128 v[130:133], v130 offset:16
	s_waitcnt lgkmcnt(3)
	v_pk_mul_f32 v[148:149], v[172:173], v[144:145]
	v_pk_mul_f32 v[146:147], v[170:171], v[142:143]
	s_waitcnt lgkmcnt(2)
	v_pk_mul_f32 v[142:143], v[172:173], v[152:153]
	v_pk_mul_f32 v[144:145], v[170:171], v[150:151]
.LBB0_232:
	s_or_b64 exec, exec, s[10:11]
	s_waitcnt lgkmcnt(6)
	v_add_f32_e32 v150, v251, v252
	v_fmamk_f32 v150, v150, 0x3a800000, v224
	v_rsq_f32_e32 v150, v150
	s_and_b64 vcc, exec, s[8:9]
	v_pk_fma_f32 v[152:153], v[128:129], v[150:151], v[72:73] op_sel_hi:[1,0,1]
	v_pk_fma_f32 v[154:155], v[126:127], v[150:151], v[70:71] op_sel_hi:[1,0,1]
	v_pk_fma_f32 v[126:127], v[124:125], v[150:151], v[68:69] op_sel_hi:[1,0,1]
	v_pk_fma_f32 v[128:129], v[122:123], v[150:151], v[66:67] op_sel_hi:[1,0,1]
	s_cbranch_vccnz .LBB0_234
	ds_bpermute_b32 v122, v187, v154
	ds_bpermute_b32 v123, v187, v155
	ds_bpermute_b32 v124, v187, v128
	ds_bpermute_b32 v156, v187, v152
	ds_bpermute_b32 v157, v187, v153
	ds_bpermute_b32 v125, v187, v129
	ds_bpermute_b32 v158, v187, v126
	ds_bpermute_b32 v159, v187, v127
	s_waitcnt lgkmcnt(6)
	v_pk_mul_f32 v[122:123], v[146:147], v[122:123]
	s_waitcnt lgkmcnt(3)
	v_pk_mul_f32 v[156:157], v[148:149], v[156:157]
	v_pk_fma_f32 v[154:155], v[154:155], v[134:135], v[122:123]
	s_waitcnt lgkmcnt(2)
	v_pk_mul_f32 v[122:123], v[144:145], v[124:125]
	s_waitcnt lgkmcnt(0)
	v_pk_mul_f32 v[124:125], v[142:143], v[158:159]
	v_pk_fma_f32 v[152:153], v[152:153], v[136:137], v[156:157]
	v_pk_fma_f32 v[126:127], v[126:127], v[132:133], v[124:125]
	v_pk_fma_f32 v[128:129], v[128:129], v[130:131], v[122:123]
.LBB0_234:
	s_not_b32 s44, s44
	v_mov_b32_e32 v124, v138
	v_mov_b32_e32 v125, v138
	v_and_b32_e32 v122, 0x1fdf, v210
	v_bitop3_b32 v156, v210, s44, v230 bitop3:0x80
	v_pk_mul_f32 v[152:153], v[124:125], v[152:153]
	v_lshrrev_b32_e32 v122, s19, v122
	v_pk_mul_f32 v[154:155], v[138:139], v[154:155]
	v_pk_mul_f32 v[158:159], v[124:125], v[126:127]
	v_cvt_pk_bf16_f32 v126, v154, v155
	v_cvt_pk_bf16_f32 v127, v152, v153
	v_add_u32_e32 v152, s47, v156
	v_lshlrev_b32_e32 v122, 7, v122
	v_mov_b32_e32 v123, v191
	v_ashrrev_i32_e32 v153, 31, v152
	v_lshl_add_u64 v[122:123], v[140:141], 0, v[122:123]
	v_lshlrev_b64 v[152:153], s17, v[152:153]
	v_pk_mul_f32 v[128:129], v[138:139], v[128:129]
	v_lshl_add_u64 v[152:153], v[152:153], 1, v[122:123]
	v_mov_b32_e32 v151, v150
	v_cvt_pk_bf16_f32 v128, v128, v129
	v_cvt_pk_bf16_f32 v129, v158, v159
	global_store_dwordx4 v[152:153], v[126:129], off
	v_pk_fma_f32 v[118:119], v[118:119], v[150:151], v[54:55]
	s_and_b64 vcc, exec, s[8:9]
	v_mov_b32_e32 v126, v150
	v_mov_b32_e32 v127, v150
	v_pk_fma_f32 v[120:121], v[120:121], v[126:127], v[56:57]
	v_pk_fma_f32 v[116:117], v[116:117], v[126:127], v[52:53]
	v_pk_fma_f32 v[114:115], v[114:115], v[150:151], v[50:51]
	s_cbranch_vccnz .LBB0_236
	ds_bpermute_b32 v126, v187, v118
	ds_bpermute_b32 v127, v187, v119
	ds_bpermute_b32 v128, v187, v114
	ds_bpermute_b32 v150, v187, v120
	ds_bpermute_b32 v151, v187, v121
	ds_bpermute_b32 v129, v187, v115
	ds_bpermute_b32 v152, v187, v116
	ds_bpermute_b32 v153, v187, v117
	s_waitcnt lgkmcnt(6)
	v_pk_mul_f32 v[126:127], v[146:147], v[126:127]
	s_waitcnt lgkmcnt(3)
	v_pk_mul_f32 v[146:147], v[148:149], v[150:151]
	v_pk_fma_f32 v[118:119], v[118:119], v[134:135], v[126:127]
	s_waitcnt lgkmcnt(2)
	v_pk_mul_f32 v[126:127], v[144:145], v[128:129]
	s_waitcnt lgkmcnt(0)
	v_pk_mul_f32 v[128:129], v[142:143], v[152:153]
	v_pk_fma_f32 v[120:121], v[120:121], v[136:137], v[146:147]
	v_pk_fma_f32 v[116:117], v[116:117], v[132:133], v[128:129]
	v_pk_fma_f32 v[114:115], v[114:115], v[130:131], v[126:127]
.LBB0_236:
	v_pk_mul_f32 v[118:119], v[138:139], v[118:119]
	v_pk_mul_f32 v[120:121], v[124:125], v[120:121]
	v_pk_mul_f32 v[124:125], v[124:125], v[116:117]
	v_pk_mul_f32 v[116:117], v[138:139], v[114:115]
	v_cvt_pk_bf16_f32 v114, v118, v119
	v_add_u32_e32 v118, s50, v156
	v_ashrrev_i32_e32 v119, 31, v118
	v_lshlrev_b64 v[118:119], s17, v[118:119]
	v_cvt_pk_bf16_f32 v115, v120, v121
	v_cvt_pk_bf16_f32 v116, v116, v117
	v_cvt_pk_bf16_f32 v117, v124, v125
	v_lshl_add_u64 v[118:119], v[118:119], 1, v[122:123]
	global_store_dwordx4 v[118:119], v[114:117], off
	v_mov_b32_e32 v126, 0
	v_mov_b32_e32 v118, 1.0
	v_mov_b32_e32 v119, 1.0
	v_mov_b32_e32 v120, 1.0
	v_mov_b32_e32 v121, 1.0
	v_mov_b32_e32 v114, 1.0
	v_mov_b32_e32 v115, 1.0
	v_mov_b32_e32 v116, 1.0
	v_mov_b32_e32 v117, 1.0
	v_mov_b32_e32 v127, 0
	v_mov_b32_e32 v128, 0
	v_mov_b32_e32 v129, 0
	v_mov_b32_e32 v124, 0
	v_mov_b32_e32 v125, 0
	v_mov_b32_e32 v122, 0
	v_mov_b32_e32 v123, 0
	s_and_saveexec_b64 s[10:11], s[42:43]
	s_cbranch_execz .LBB0_238
	v_and_b32_e32 v114, 0x3fc0, v208
	v_add_u32_e32 v114, 0x21000, v114
	ds_read_b128 v[122:125], v114 offset:32
	ds_read_b128 v[130:133], v114 offset:48
	ds_read_b128 v[118:121], v114
	s_nop 0
	ds_read_b128 v[114:117], v114 offset:16
	s_waitcnt lgkmcnt(3)
	v_pk_mul_f32 v[128:129], v[172:173], v[124:125]
	v_pk_mul_f32 v[126:127], v[170:171], v[122:123]
	s_waitcnt lgkmcnt(2)
	v_pk_mul_f32 v[122:123], v[172:173], v[132:133]
	v_pk_mul_f32 v[124:125], v[170:171], v[130:131]
.LBB0_238:
	s_or_b64 exec, exec, s[10:11]
	s_waitcnt lgkmcnt(5)
	v_add_f32_e32 v130, v249, v250
	v_fmamk_f32 v130, v130, 0x3a800000, v224
	v_rsq_f32_e32 v130, v130
	s_and_b64 vcc, exec, s[8:9]
	v_pk_fma_f32 v[132:133], v[112:113], v[130:131], v[72:73] op_sel_hi:[1,0,1]
	v_pk_fma_f32 v[134:135], v[110:111], v[130:131], v[70:71] op_sel_hi:[1,0,1]
	v_pk_fma_f32 v[110:111], v[108:109], v[130:131], v[68:69] op_sel_hi:[1,0,1]
	v_pk_fma_f32 v[112:113], v[106:107], v[130:131], v[66:67] op_sel_hi:[1,0,1]
	s_cbranch_vccnz .LBB0_240
	ds_bpermute_b32 v106, v187, v134
	ds_bpermute_b32 v107, v187, v135
	ds_bpermute_b32 v108, v187, v112
	ds_bpermute_b32 v136, v187, v132
	ds_bpermute_b32 v137, v187, v133
	ds_bpermute_b32 v109, v187, v113
	ds_bpermute_b32 v142, v187, v110
	ds_bpermute_b32 v143, v187, v111
	s_waitcnt lgkmcnt(6)
	v_pk_mul_f32 v[106:107], v[126:127], v[106:107]
	s_waitcnt lgkmcnt(3)
	v_pk_mul_f32 v[136:137], v[128:129], v[136:137]
	v_pk_fma_f32 v[134:135], v[134:135], v[118:119], v[106:107]
	s_waitcnt lgkmcnt(2)
	v_pk_mul_f32 v[106:107], v[124:125], v[108:109]
	s_waitcnt lgkmcnt(0)
	v_pk_mul_f32 v[108:109], v[122:123], v[142:143]
	v_pk_fma_f32 v[132:133], v[132:133], v[120:121], v[136:137]
	v_pk_fma_f32 v[110:111], v[110:111], v[116:117], v[108:109]
	v_pk_fma_f32 v[112:113], v[112:113], v[114:115], v[106:107]
.LBB0_240:
	v_mov_b32_e32 v108, v138
	v_mov_b32_e32 v109, v138
	v_and_b32_e32 v106, 0x1fef, v206
	v_bitop3_b32 v136, v206, s44, v231 bitop3:0x80
	v_pk_mul_f32 v[132:133], v[108:109], v[132:133]
	v_lshrrev_b32_e32 v106, s19, v106
	v_pk_mul_f32 v[134:135], v[138:139], v[134:135]
	v_pk_mul_f32 v[142:143], v[108:109], v[110:111]
	v_cvt_pk_bf16_f32 v110, v134, v135
	v_cvt_pk_bf16_f32 v111, v132, v133
	v_add_u32_e32 v132, s47, v136
	v_lshlrev_b32_e32 v106, 7, v106
	v_mov_b32_e32 v107, v191
	v_ashrrev_i32_e32 v133, 31, v132
	v_lshl_add_u64 v[106:107], v[140:141], 0, v[106:107]
	v_lshlrev_b64 v[132:133], s17, v[132:133]
	v_pk_mul_f32 v[112:113], v[138:139], v[112:113]
	v_lshl_add_u64 v[132:133], v[132:133], 1, v[106:107]
	v_mov_b32_e32 v131, v130
	v_cvt_pk_bf16_f32 v112, v112, v113
	v_cvt_pk_bf16_f32 v113, v142, v143
	global_store_dwordx4 v[132:133], v[110:113], off
	v_pk_fma_f32 v[102:103], v[102:103], v[130:131], v[54:55]
	s_and_b64 vcc, exec, s[8:9]
	v_mov_b32_e32 v110, v130
	v_mov_b32_e32 v111, v130
	v_pk_fma_f32 v[104:105], v[104:105], v[110:111], v[56:57]
	v_pk_fma_f32 v[100:101], v[100:101], v[110:111], v[52:53]
	v_pk_fma_f32 v[98:99], v[98:99], v[130:131], v[50:51]
	s_cbranch_vccnz .LBB0_242
	ds_bpermute_b32 v110, v187, v102
	ds_bpermute_b32 v111, v187, v103
	ds_bpermute_b32 v112, v187, v98
	ds_bpermute_b32 v130, v187, v104
	ds_bpermute_b32 v131, v187, v105
	ds_bpermute_b32 v113, v187, v99
	ds_bpermute_b32 v132, v187, v100
	ds_bpermute_b32 v133, v187, v101
	s_waitcnt lgkmcnt(6)
	v_pk_mul_f32 v[110:111], v[126:127], v[110:111]
	s_waitcnt lgkmcnt(3)
	v_pk_mul_f32 v[126:127], v[128:129], v[130:131]
	v_pk_fma_f32 v[102:103], v[102:103], v[118:119], v[110:111]
	s_waitcnt lgkmcnt(2)
	v_pk_mul_f32 v[110:111], v[124:125], v[112:113]
	s_waitcnt lgkmcnt(0)
	v_pk_mul_f32 v[112:113], v[122:123], v[132:133]
	v_pk_fma_f32 v[104:105], v[104:105], v[120:121], v[126:127]
	v_pk_fma_f32 v[100:101], v[100:101], v[116:117], v[112:113]
	v_pk_fma_f32 v[98:99], v[98:99], v[114:115], v[110:111]
.LBB0_242:
	v_pk_mul_f32 v[102:103], v[138:139], v[102:103]
	v_pk_mul_f32 v[104:105], v[108:109], v[104:105]
	v_pk_mul_f32 v[108:109], v[108:109], v[100:101]
	v_pk_mul_f32 v[100:101], v[138:139], v[98:99]
	v_cvt_pk_bf16_f32 v98, v102, v103
	v_add_u32_e32 v102, s50, v136
	v_ashrrev_i32_e32 v103, 31, v102
	v_lshlrev_b64 v[102:103], s17, v[102:103]
	v_cvt_pk_bf16_f32 v99, v104, v105
	v_cvt_pk_bf16_f32 v100, v100, v101
	v_cvt_pk_bf16_f32 v101, v108, v109
	v_lshl_add_u64 v[102:103], v[102:103], 1, v[106:107]
	global_store_dwordx4 v[102:103], v[98:101], off
	v_mov_b32_e32 v110, 0
	v_mov_b32_e32 v102, 1.0
	v_mov_b32_e32 v103, 1.0
	v_mov_b32_e32 v104, 1.0
	v_mov_b32_e32 v105, 1.0
	v_mov_b32_e32 v98, 1.0
	v_mov_b32_e32 v99, 1.0
	v_mov_b32_e32 v100, 1.0
	v_mov_b32_e32 v101, 1.0
	v_mov_b32_e32 v111, 0
	v_mov_b32_e32 v112, 0
	v_mov_b32_e32 v113, 0
	v_mov_b32_e32 v108, 0
	v_mov_b32_e32 v109, 0
	v_mov_b32_e32 v106, 0
	v_mov_b32_e32 v107, 0
	s_and_saveexec_b64 s[10:11], s[42:43]
	s_cbranch_execz .LBB0_244
	v_and_b32_e32 v98, 0x3fc0, v204
	v_add_u32_e32 v98, 0x21000, v98
	ds_read_b128 v[106:109], v98 offset:32
	ds_read_b128 v[114:117], v98 offset:48
	ds_read_b128 v[102:105], v98
	s_nop 0
	ds_read_b128 v[98:101], v98 offset:16
	s_waitcnt lgkmcnt(3)
	v_pk_mul_f32 v[112:113], v[172:173], v[108:109]
	v_pk_mul_f32 v[110:111], v[170:171], v[106:107]
	s_waitcnt lgkmcnt(2)
	v_pk_mul_f32 v[106:107], v[172:173], v[116:117]
	v_pk_mul_f32 v[108:109], v[170:171], v[114:115]
.LBB0_244:
	s_or_b64 exec, exec, s[10:11]
	s_waitcnt lgkmcnt(4)
	v_add_f32_e32 v114, v247, v248
	v_fmamk_f32 v114, v114, 0x3a800000, v224
	v_rsq_f32_e32 v114, v114
	s_and_b64 vcc, exec, s[8:9]
	v_pk_fma_f32 v[116:117], v[96:97], v[114:115], v[72:73] op_sel_hi:[1,0,1]
	v_pk_fma_f32 v[118:119], v[94:95], v[114:115], v[70:71] op_sel_hi:[1,0,1]
	v_pk_fma_f32 v[94:95], v[92:93], v[114:115], v[68:69] op_sel_hi:[1,0,1]
	v_pk_fma_f32 v[96:97], v[90:91], v[114:115], v[66:67] op_sel_hi:[1,0,1]
	s_cbranch_vccnz .LBB0_246
	ds_bpermute_b32 v90, v187, v118
	ds_bpermute_b32 v91, v187, v119
	ds_bpermute_b32 v92, v187, v96
	ds_bpermute_b32 v120, v187, v116
	ds_bpermute_b32 v121, v187, v117
	ds_bpermute_b32 v93, v187, v97
	ds_bpermute_b32 v122, v187, v94
	ds_bpermute_b32 v123, v187, v95
	s_waitcnt lgkmcnt(6)
	v_pk_mul_f32 v[90:91], v[110:111], v[90:91]
	s_waitcnt lgkmcnt(3)
	v_pk_mul_f32 v[120:121], v[112:113], v[120:121]
	v_pk_fma_f32 v[118:119], v[118:119], v[102:103], v[90:91]
	s_waitcnt lgkmcnt(2)
	v_pk_mul_f32 v[90:91], v[108:109], v[92:93]
	s_waitcnt lgkmcnt(0)
	v_pk_mul_f32 v[92:93], v[106:107], v[122:123]
	v_pk_fma_f32 v[116:117], v[116:117], v[104:105], v[120:121]
	v_pk_fma_f32 v[94:95], v[94:95], v[100:101], v[92:93]
	v_pk_fma_f32 v[96:97], v[96:97], v[98:99], v[90:91]
.LBB0_246:
	v_mov_b32_e32 v92, v138
	v_mov_b32_e32 v93, v138
	v_and_b32_e32 v90, 0x1fff, v202
	v_bitop3_b32 v120, v202, s44, v232 bitop3:0x80
	v_pk_mul_f32 v[116:117], v[92:93], v[116:117]
	v_lshrrev_b32_e32 v90, s19, v90
	v_pk_mul_f32 v[118:119], v[138:139], v[118:119]
	v_pk_mul_f32 v[122:123], v[92:93], v[94:95]
	v_cvt_pk_bf16_f32 v94, v118, v119
	v_cvt_pk_bf16_f32 v95, v116, v117
	v_add_u32_e32 v116, s47, v120
	v_lshlrev_b32_e32 v90, 7, v90
	v_mov_b32_e32 v91, v191
	v_ashrrev_i32_e32 v117, 31, v116
	v_lshl_add_u64 v[90:91], v[140:141], 0, v[90:91]
	v_lshlrev_b64 v[116:117], s17, v[116:117]
	v_pk_mul_f32 v[96:97], v[138:139], v[96:97]
	v_lshl_add_u64 v[116:117], v[116:117], 1, v[90:91]
	v_mov_b32_e32 v115, v114
	v_cvt_pk_bf16_f32 v96, v96, v97
	v_cvt_pk_bf16_f32 v97, v122, v123
	global_store_dwordx4 v[116:117], v[94:97], off
	v_pk_fma_f32 v[86:87], v[86:87], v[114:115], v[54:55]
	s_and_b64 vcc, exec, s[8:9]
	v_mov_b32_e32 v94, v114
	v_mov_b32_e32 v95, v114
	v_pk_fma_f32 v[88:89], v[88:89], v[94:95], v[56:57]
	v_pk_fma_f32 v[84:85], v[84:85], v[94:95], v[52:53]
	v_pk_fma_f32 v[82:83], v[82:83], v[114:115], v[50:51]
	s_cbranch_vccnz .LBB0_248
	ds_bpermute_b32 v94, v187, v86
	ds_bpermute_b32 v95, v187, v87
	ds_bpermute_b32 v96, v187, v82
	ds_bpermute_b32 v114, v187, v88
	ds_bpermute_b32 v115, v187, v89
	ds_bpermute_b32 v97, v187, v83
	ds_bpermute_b32 v116, v187, v84
	ds_bpermute_b32 v117, v187, v85
	s_waitcnt lgkmcnt(6)
	v_pk_mul_f32 v[94:95], v[110:111], v[94:95]
	s_waitcnt lgkmcnt(3)
	v_pk_mul_f32 v[110:111], v[112:113], v[114:115]
	v_pk_fma_f32 v[86:87], v[86:87], v[102:103], v[94:95]
	s_waitcnt lgkmcnt(2)
	v_pk_mul_f32 v[94:95], v[108:109], v[96:97]
	s_waitcnt lgkmcnt(0)
	v_pk_mul_f32 v[96:97], v[106:107], v[116:117]
	v_pk_fma_f32 v[88:89], v[88:89], v[104:105], v[110:111]
	v_pk_fma_f32 v[84:85], v[84:85], v[100:101], v[96:97]
	v_pk_fma_f32 v[82:83], v[82:83], v[98:99], v[94:95]
.LBB0_248:
	v_pk_mul_f32 v[86:87], v[138:139], v[86:87]
	v_pk_mul_f32 v[88:89], v[92:93], v[88:89]
	v_pk_mul_f32 v[92:93], v[92:93], v[84:85]
	v_pk_mul_f32 v[84:85], v[138:139], v[82:83]
	v_cvt_pk_bf16_f32 v82, v86, v87
	v_add_u32_e32 v86, s50, v120
	v_ashrrev_i32_e32 v87, 31, v86
	v_lshlrev_b64 v[86:87], s17, v[86:87]
	v_cvt_pk_bf16_f32 v83, v88, v89
	v_cvt_pk_bf16_f32 v84, v84, v85
	v_cvt_pk_bf16_f32 v85, v92, v93
	v_lshl_add_u64 v[86:87], v[86:87], 1, v[90:91]
	global_store_dwordx4 v[86:87], v[82:85], off
	v_mov_b32_e32 v94, 0
	v_mov_b32_e32 v86, 1.0
	v_mov_b32_e32 v87, 1.0
	v_mov_b32_e32 v88, 1.0
	v_mov_b32_e32 v89, 1.0
	v_mov_b32_e32 v82, 1.0
	v_mov_b32_e32 v83, 1.0
	v_mov_b32_e32 v84, 1.0
	v_mov_b32_e32 v85, 1.0
	v_mov_b32_e32 v95, 0
	v_mov_b32_e32 v96, 0
	v_mov_b32_e32 v97, 0
	v_mov_b32_e32 v92, 0
	v_mov_b32_e32 v93, 0
	v_mov_b32_e32 v90, 0
	v_mov_b32_e32 v91, 0
	s_and_saveexec_b64 s[10:11], s[42:43]
	s_cbranch_execz .LBB0_250
	v_and_b32_e32 v82, 0x3fc0, v188
	v_add_u32_e32 v82, 0x21000, v82
	ds_read_b128 v[90:93], v82 offset:32
	ds_read_b128 v[98:101], v82 offset:48
	ds_read_b128 v[86:89], v82
	s_nop 0
	ds_read_b128 v[82:85], v82 offset:16
	s_waitcnt lgkmcnt(3)
	v_pk_mul_f32 v[96:97], v[172:173], v[92:93]
	v_pk_mul_f32 v[94:95], v[170:171], v[90:91]
	s_waitcnt lgkmcnt(2)
	v_pk_mul_f32 v[90:91], v[172:173], v[100:101]
	v_pk_mul_f32 v[92:93], v[170:171], v[98:99]
.LBB0_250:
	s_or_b64 exec, exec, s[10:11]
	s_waitcnt lgkmcnt(3)
	v_add_f32_e32 v98, v245, v246
	v_fmamk_f32 v98, v98, 0x3a800000, v224
	v_rsq_f32_e32 v98, v98
	s_and_b64 vcc, exec, s[8:9]
	v_pk_fma_f32 v[100:101], v[80:81], v[98:99], v[72:73] op_sel_hi:[1,0,1]
	v_pk_fma_f32 v[102:103], v[78:79], v[98:99], v[70:71] op_sel_hi:[1,0,1]
	v_pk_fma_f32 v[78:79], v[76:77], v[98:99], v[68:69] op_sel_hi:[1,0,1]
	v_pk_fma_f32 v[80:81], v[74:75], v[98:99], v[66:67] op_sel_hi:[1,0,1]
	s_cbranch_vccnz .LBB0_252
	ds_bpermute_b32 v74, v187, v102
	ds_bpermute_b32 v75, v187, v103
	ds_bpermute_b32 v76, v187, v80
	ds_bpermute_b32 v104, v187, v100
	ds_bpermute_b32 v105, v187, v101
	ds_bpermute_b32 v77, v187, v81
	ds_bpermute_b32 v106, v187, v78
	ds_bpermute_b32 v107, v187, v79
	s_waitcnt lgkmcnt(6)
	v_pk_mul_f32 v[74:75], v[94:95], v[74:75]
	s_waitcnt lgkmcnt(3)
	v_pk_mul_f32 v[104:105], v[96:97], v[104:105]
	v_pk_fma_f32 v[102:103], v[102:103], v[86:87], v[74:75]
	s_waitcnt lgkmcnt(2)
	v_pk_mul_f32 v[74:75], v[92:93], v[76:77]
	s_waitcnt lgkmcnt(0)
	v_pk_mul_f32 v[76:77], v[90:91], v[106:107]
	v_pk_fma_f32 v[100:101], v[100:101], v[88:89], v[104:105]
	v_pk_fma_f32 v[78:79], v[78:79], v[84:85], v[76:77]
	v_pk_fma_f32 v[80:81], v[80:81], v[82:83], v[74:75]
.LBB0_252:
	v_ashrrev_i32_e32 v76, 13, v186
	v_mad_i32_i24 v105, v76, 24, s46
	v_mov_b32_e32 v76, v138
	v_mov_b32_e32 v77, v138
	v_pk_mul_f32 v[100:101], v[76:77], v[100:101]
	v_and_b32_e32 v74, 0x1fcf, v186
	v_bitop3_b32 v104, v186, s44, v229 bitop3:0x80
	v_pk_mul_f32 v[102:103], v[138:139], v[102:103]
	v_pk_mul_f32 v[106:107], v[76:77], v[78:79]
	v_cvt_pk_bf16_f32 v78, v102, v103
	v_cvt_pk_bf16_f32 v79, v100, v101
	v_lshlrev_b32_e32 v100, s19, v105
	v_lshrrev_b32_e32 v74, s19, v74
	v_add_u32_e32 v102, v100, v104
	v_lshlrev_b32_e32 v74, 7, v74
	v_mov_b32_e32 v75, v191
	v_ashrrev_i32_e32 v103, 31, v102
	v_lshl_add_u64 v[74:75], v[140:141], 0, v[74:75]
	v_lshlrev_b64 v[102:103], s17, v[102:103]
	v_pk_mul_f32 v[80:81], v[138:139], v[80:81]
	v_lshl_add_u64 v[102:103], v[102:103], 1, v[74:75]
	v_mov_b32_e32 v99, v98
	v_cvt_pk_bf16_f32 v80, v80, v81
	v_cvt_pk_bf16_f32 v81, v106, v107
	global_store_dwordx4 v[102:103], v[78:81], off
	v_pk_fma_f32 v[62:63], v[62:63], v[98:99], v[54:55]
	s_and_b64 vcc, exec, s[8:9]
	v_mov_b32_e32 v78, v98
	v_mov_b32_e32 v79, v98
	v_pk_fma_f32 v[64:65], v[64:65], v[78:79], v[56:57]
	v_pk_fma_f32 v[60:61], v[60:61], v[78:79], v[52:53]
	v_pk_fma_f32 v[58:59], v[58:59], v[98:99], v[50:51]
	s_cbranch_vccnz .LBB0_254
	ds_bpermute_b32 v78, v187, v62
	ds_bpermute_b32 v79, v187, v63
	ds_bpermute_b32 v80, v187, v58
	ds_bpermute_b32 v98, v187, v64
	ds_bpermute_b32 v99, v187, v65
	ds_bpermute_b32 v81, v187, v59
	ds_bpermute_b32 v102, v187, v60
	ds_bpermute_b32 v103, v187, v61
	s_waitcnt lgkmcnt(6)
	v_pk_mul_f32 v[78:79], v[94:95], v[78:79]
	s_waitcnt lgkmcnt(3)
	v_pk_mul_f32 v[94:95], v[96:97], v[98:99]
	v_pk_fma_f32 v[62:63], v[62:63], v[86:87], v[78:79]
	s_waitcnt lgkmcnt(2)
	v_pk_mul_f32 v[78:79], v[92:93], v[80:81]
	s_waitcnt lgkmcnt(0)
	v_pk_mul_f32 v[80:81], v[90:91], v[102:103]
	v_pk_fma_f32 v[64:65], v[64:65], v[88:89], v[94:95]
	v_pk_fma_f32 v[60:61], v[60:61], v[84:85], v[80:81]
	v_pk_fma_f32 v[58:59], v[58:59], v[82:83], v[78:79]
.LBB0_254:
	v_pk_mul_f32 v[62:63], v[138:139], v[62:63]
	v_pk_mul_f32 v[64:65], v[76:77], v[64:65]
	v_pk_mul_f32 v[76:77], v[76:77], v[60:61]
	v_pk_mul_f32 v[60:61], v[138:139], v[58:59]
	v_cvt_pk_bf16_f32 v58, v62, v63
	v_or_b32_e32 v62, 2, v105
	v_lshlrev_b32_e32 v88, s19, v62
	v_add_u32_e32 v62, v88, v104
	v_ashrrev_i32_e32 v63, 31, v62
	v_lshlrev_b64 v[62:63], s17, v[62:63]
	v_cvt_pk_bf16_f32 v59, v64, v65
	v_cvt_pk_bf16_f32 v60, v60, v61
	v_cvt_pk_bf16_f32 v61, v76, v77
	v_lshl_add_u64 v[62:63], v[62:63], 1, v[74:75]
	global_store_dwordx4 v[62:63], v[58:61], off
	v_mov_b32_e32 v78, 0
	v_mov_b32_e32 v62, 1.0
	v_mov_b32_e32 v63, 1.0
	v_mov_b32_e32 v64, 1.0
	v_mov_b32_e32 v65, 1.0
	v_mov_b32_e32 v58, 1.0
	v_mov_b32_e32 v59, 1.0
	v_mov_b32_e32 v60, 1.0
	v_mov_b32_e32 v61, 1.0
	v_mov_b32_e32 v79, 0
	v_mov_b32_e32 v80, 0
	v_mov_b32_e32 v81, 0
	v_mov_b32_e32 v76, 0
	v_mov_b32_e32 v77, 0
	v_mov_b32_e32 v74, 0
	v_mov_b32_e32 v75, 0
	s_and_saveexec_b64 s[10:11], s[42:43]
	s_cbranch_execz .LBB0_256
	v_lshlrev_b64 v[58:59], 6, v[184:185]
	v_and_b32_e32 v58, 0x3fc0, v58
	v_add_u32_e32 v58, 0x21000, v58
	ds_read_b128 v[74:77], v58 offset:32
	ds_read_b128 v[82:85], v58 offset:48
	ds_read_b128 v[62:65], v58
	s_nop 0
	ds_read_b128 v[58:61], v58 offset:16
	s_waitcnt lgkmcnt(3)
	v_pk_mul_f32 v[80:81], v[172:173], v[76:77]
	v_pk_mul_f32 v[78:79], v[170:171], v[74:75]
	s_waitcnt lgkmcnt(2)
	v_pk_mul_f32 v[74:75], v[172:173], v[84:85]
	v_pk_mul_f32 v[76:77], v[170:171], v[82:83]
.LBB0_256:
	s_or_b64 exec, exec, s[10:11]
	s_waitcnt lgkmcnt(2)
	v_add_f32_e32 v82, v243, v244
	v_fmamk_f32 v82, v82, 0x3a800000, v224
	v_rsq_f32_e32 v82, v82
	s_and_b64 vcc, exec, s[8:9]
	v_pk_fma_f32 v[84:85], v[48:49], v[82:83], v[72:73] op_sel_hi:[1,0,1]
	v_pk_fma_f32 v[86:87], v[46:47], v[82:83], v[70:71] op_sel_hi:[1,0,1]
	v_pk_fma_f32 v[46:47], v[44:45], v[82:83], v[68:69] op_sel_hi:[1,0,1]
	v_pk_fma_f32 v[48:49], v[42:43], v[82:83], v[66:67] op_sel_hi:[1,0,1]
	s_cbranch_vccnz .LBB0_258
	ds_bpermute_b32 v42, v187, v86
	ds_bpermute_b32 v43, v187, v87
	ds_bpermute_b32 v44, v187, v48
	ds_bpermute_b32 v90, v187, v84
	ds_bpermute_b32 v91, v187, v85
	ds_bpermute_b32 v45, v187, v49
	ds_bpermute_b32 v92, v187, v46
	ds_bpermute_b32 v93, v187, v47
	s_waitcnt lgkmcnt(6)
	v_pk_mul_f32 v[42:43], v[78:79], v[42:43]
	s_waitcnt lgkmcnt(3)
	v_pk_mul_f32 v[90:91], v[80:81], v[90:91]
	v_pk_fma_f32 v[86:87], v[86:87], v[62:63], v[42:43]
	s_waitcnt lgkmcnt(2)
	v_pk_mul_f32 v[42:43], v[76:77], v[44:45]
	s_waitcnt lgkmcnt(0)
	v_pk_mul_f32 v[44:45], v[74:75], v[92:93]
	v_pk_fma_f32 v[84:85], v[84:85], v[64:65], v[90:91]
	v_pk_fma_f32 v[46:47], v[46:47], v[60:61], v[44:45]
	v_pk_fma_f32 v[48:49], v[48:49], v[58:59], v[42:43]
.LBB0_258:
	v_mov_b32_e32 v44, v138
	v_mov_b32_e32 v45, v138
	v_and_b32_e32 v42, 0x1fdf, v184
	v_bitop3_b32 v89, v184, s44, v230 bitop3:0x80
	v_pk_mul_f32 v[84:85], v[44:45], v[84:85]
	v_lshrrev_b32_e32 v42, s19, v42
	v_pk_mul_f32 v[86:87], v[138:139], v[86:87]
	v_pk_mul_f32 v[90:91], v[44:45], v[46:47]
	v_cvt_pk_bf16_f32 v46, v86, v87
	v_cvt_pk_bf16_f32 v47, v84, v85
	v_add_u32_e32 v84, v100, v89
	v_lshlrev_b32_e32 v42, 7, v42
	v_mov_b32_e32 v43, v191
	v_ashrrev_i32_e32 v85, 31, v84
	v_lshl_add_u64 v[42:43], v[140:141], 0, v[42:43]
	v_lshlrev_b64 v[84:85], s17, v[84:85]
	v_pk_mul_f32 v[48:49], v[138:139], v[48:49]
	v_lshl_add_u64 v[84:85], v[84:85], 1, v[42:43]
	v_mov_b32_e32 v83, v82
	v_cvt_pk_bf16_f32 v48, v48, v49
	v_cvt_pk_bf16_f32 v49, v90, v91
	global_store_dwordx4 v[84:85], v[46:49], off
	v_pk_fma_f32 v[38:39], v[38:39], v[82:83], v[54:55]
	s_and_b64 vcc, exec, s[8:9]
	v_mov_b32_e32 v46, v82
	v_mov_b32_e32 v47, v82
	v_pk_fma_f32 v[40:41], v[40:41], v[46:47], v[56:57]
	v_pk_fma_f32 v[36:37], v[36:37], v[46:47], v[52:53]
	v_pk_fma_f32 v[34:35], v[34:35], v[82:83], v[50:51]
	s_cbranch_vccnz .LBB0_260
	ds_bpermute_b32 v46, v187, v38
	ds_bpermute_b32 v47, v187, v39
	ds_bpermute_b32 v48, v187, v34
	ds_bpermute_b32 v82, v187, v40
	ds_bpermute_b32 v83, v187, v41
	ds_bpermute_b32 v49, v187, v35
	ds_bpermute_b32 v84, v187, v36
	ds_bpermute_b32 v85, v187, v37
	s_waitcnt lgkmcnt(6)
	v_pk_mul_f32 v[46:47], v[78:79], v[46:47]
	s_waitcnt lgkmcnt(3)
	v_pk_mul_f32 v[78:79], v[80:81], v[82:83]
	v_pk_fma_f32 v[38:39], v[38:39], v[62:63], v[46:47]
	s_waitcnt lgkmcnt(2)
	v_pk_mul_f32 v[46:47], v[76:77], v[48:49]
	s_waitcnt lgkmcnt(0)
	v_pk_mul_f32 v[48:49], v[74:75], v[84:85]
	v_pk_fma_f32 v[40:41], v[40:41], v[64:65], v[78:79]
	v_pk_fma_f32 v[36:37], v[36:37], v[60:61], v[48:49]
	v_pk_fma_f32 v[34:35], v[34:35], v[58:59], v[46:47]
.LBB0_260:
	v_pk_mul_f32 v[38:39], v[138:139], v[38:39]
	v_pk_mul_f32 v[40:41], v[44:45], v[40:41]
	v_pk_mul_f32 v[44:45], v[44:45], v[36:37]
	v_pk_mul_f32 v[36:37], v[138:139], v[34:35]
	v_cvt_pk_bf16_f32 v34, v38, v39
	v_add_u32_e32 v38, v88, v89
	v_ashrrev_i32_e32 v39, 31, v38
	v_lshlrev_b64 v[38:39], s17, v[38:39]
	v_cvt_pk_bf16_f32 v35, v40, v41
	v_cvt_pk_bf16_f32 v36, v36, v37
	v_cvt_pk_bf16_f32 v37, v44, v45
	v_lshl_add_u64 v[38:39], v[38:39], 1, v[42:43]
	global_store_dwordx4 v[38:39], v[34:37], off
	v_mov_b32_e32 v46, 0
	v_mov_b32_e32 v38, 1.0
	v_mov_b32_e32 v39, 1.0
	v_mov_b32_e32 v40, 1.0
	v_mov_b32_e32 v41, 1.0
	v_mov_b32_e32 v34, 1.0
	v_mov_b32_e32 v35, 1.0
	v_mov_b32_e32 v36, 1.0
	v_mov_b32_e32 v37, 1.0
	v_mov_b32_e32 v47, 0
	v_mov_b32_e32 v48, 0
	v_mov_b32_e32 v49, 0
	v_mov_b32_e32 v44, 0
	v_mov_b32_e32 v45, 0
	v_mov_b32_e32 v42, 0
	v_mov_b32_e32 v43, 0
	s_and_saveexec_b64 s[10:11], s[42:43]
	s_cbranch_execz .LBB0_262
	v_lshlrev_b64 v[34:35], 6, v[182:183]
	v_and_b32_e32 v34, 0x3fc0, v34
	v_add_u32_e32 v34, 0x21000, v34
	ds_read_b128 v[42:45], v34 offset:32
	ds_read_b128 v[58:61], v34 offset:48
	ds_read_b128 v[38:41], v34
	s_nop 0
	ds_read_b128 v[34:37], v34 offset:16
	s_waitcnt lgkmcnt(3)
	v_pk_mul_f32 v[48:49], v[172:173], v[44:45]
	v_pk_mul_f32 v[46:47], v[170:171], v[42:43]
	s_waitcnt lgkmcnt(2)
	v_pk_mul_f32 v[42:43], v[172:173], v[60:61]
	v_pk_mul_f32 v[44:45], v[170:171], v[58:59]
.LBB0_262:
	s_or_b64 exec, exec, s[10:11]
	s_waitcnt lgkmcnt(1)
	v_add_f32_e32 v58, v211, v215
	v_fmamk_f32 v58, v58, 0x3a800000, v224
	v_rsq_f32_e32 v58, v58
	s_and_b64 vcc, exec, s[8:9]
	v_pk_fma_f32 v[60:61], v[32:33], v[58:59], v[72:73] op_sel_hi:[1,0,1]
	v_pk_fma_f32 v[62:63], v[30:31], v[58:59], v[70:71] op_sel_hi:[1,0,1]
	v_pk_fma_f32 v[30:31], v[28:29], v[58:59], v[68:69] op_sel_hi:[1,0,1]
	v_pk_fma_f32 v[32:33], v[26:27], v[58:59], v[66:67] op_sel_hi:[1,0,1]
	s_cbranch_vccnz .LBB0_264
	ds_bpermute_b32 v26, v187, v62
	ds_bpermute_b32 v27, v187, v63
	ds_bpermute_b32 v28, v187, v32
	ds_bpermute_b32 v64, v187, v60
	ds_bpermute_b32 v65, v187, v61
	ds_bpermute_b32 v29, v187, v33
	ds_bpermute_b32 v74, v187, v30
	ds_bpermute_b32 v75, v187, v31
	s_waitcnt lgkmcnt(6)
	v_pk_mul_f32 v[26:27], v[46:47], v[26:27]
	s_waitcnt lgkmcnt(3)
	v_pk_mul_f32 v[64:65], v[48:49], v[64:65]
	v_pk_fma_f32 v[62:63], v[62:63], v[38:39], v[26:27]
	s_waitcnt lgkmcnt(2)
	v_pk_mul_f32 v[26:27], v[44:45], v[28:29]
	s_waitcnt lgkmcnt(0)
	v_pk_mul_f32 v[28:29], v[42:43], v[74:75]
	v_pk_fma_f32 v[60:61], v[60:61], v[40:41], v[64:65]
	v_pk_fma_f32 v[30:31], v[30:31], v[36:37], v[28:29]
	v_pk_fma_f32 v[32:33], v[32:33], v[34:35], v[26:27]
.LBB0_264:
	v_mov_b32_e32 v28, v138
	v_mov_b32_e32 v29, v138
	v_and_b32_e32 v26, 0x1fef, v182
	v_bitop3_b32 v64, v182, s44, v231 bitop3:0x80
	v_pk_mul_f32 v[60:61], v[28:29], v[60:61]
	v_lshrrev_b32_e32 v26, s19, v26
	v_pk_mul_f32 v[62:63], v[138:139], v[62:63]
	v_pk_mul_f32 v[74:75], v[28:29], v[30:31]
	v_cvt_pk_bf16_f32 v30, v62, v63
	v_cvt_pk_bf16_f32 v31, v60, v61
	v_add_u32_e32 v60, v100, v64
	v_lshlrev_b32_e32 v26, 7, v26
	v_mov_b32_e32 v27, v191
	v_ashrrev_i32_e32 v61, 31, v60
	v_lshl_add_u64 v[26:27], v[140:141], 0, v[26:27]
	v_lshlrev_b64 v[60:61], s17, v[60:61]
	v_pk_mul_f32 v[32:33], v[138:139], v[32:33]
	v_lshl_add_u64 v[60:61], v[60:61], 1, v[26:27]
	v_mov_b32_e32 v59, v58
	v_cvt_pk_bf16_f32 v32, v32, v33
	v_cvt_pk_bf16_f32 v33, v74, v75
	global_store_dwordx4 v[60:61], v[30:33], off
	v_pk_fma_f32 v[22:23], v[22:23], v[58:59], v[54:55]
	s_and_b64 vcc, exec, s[8:9]
	v_mov_b32_e32 v30, v58
	v_mov_b32_e32 v31, v58
	v_pk_fma_f32 v[24:25], v[24:25], v[30:31], v[56:57]
	v_pk_fma_f32 v[20:21], v[20:21], v[30:31], v[52:53]
	v_pk_fma_f32 v[18:19], v[18:19], v[58:59], v[50:51]
	s_cbranch_vccnz .LBB0_266
	ds_bpermute_b32 v30, v187, v22
	ds_bpermute_b32 v31, v187, v23
	ds_bpermute_b32 v32, v187, v18
	ds_bpermute_b32 v58, v187, v24
	ds_bpermute_b32 v59, v187, v25
	ds_bpermute_b32 v33, v187, v19
	ds_bpermute_b32 v60, v187, v20
	ds_bpermute_b32 v61, v187, v21
	s_waitcnt lgkmcnt(6)
	v_pk_mul_f32 v[30:31], v[46:47], v[30:31]
	s_waitcnt lgkmcnt(3)
	v_pk_mul_f32 v[46:47], v[48:49], v[58:59]
	v_pk_fma_f32 v[22:23], v[22:23], v[38:39], v[30:31]
	s_waitcnt lgkmcnt(2)
	v_pk_mul_f32 v[30:31], v[44:45], v[32:33]
	s_waitcnt lgkmcnt(0)
	v_pk_mul_f32 v[32:33], v[42:43], v[60:61]
	v_pk_fma_f32 v[24:25], v[24:25], v[40:41], v[46:47]
	v_pk_fma_f32 v[20:21], v[20:21], v[36:37], v[32:33]
	v_pk_fma_f32 v[18:19], v[18:19], v[34:35], v[30:31]
.LBB0_266:
	v_pk_mul_f32 v[22:23], v[138:139], v[22:23]
	v_pk_mul_f32 v[24:25], v[28:29], v[24:25]
	v_pk_mul_f32 v[28:29], v[28:29], v[20:21]
	v_pk_mul_f32 v[20:21], v[138:139], v[18:19]
	v_cvt_pk_bf16_f32 v18, v22, v23
	v_add_u32_e32 v22, v88, v64
	v_ashrrev_i32_e32 v23, 31, v22
	v_lshlrev_b64 v[22:23], s17, v[22:23]
	v_cvt_pk_bf16_f32 v19, v24, v25
	v_cvt_pk_bf16_f32 v20, v20, v21
	v_cvt_pk_bf16_f32 v21, v28, v29
	v_lshl_add_u64 v[22:23], v[22:23], 1, v[26:27]
	global_store_dwordx4 v[22:23], v[18:21], off
	v_mov_b32_e32 v30, 0
	v_mov_b32_e32 v22, 1.0
	v_mov_b32_e32 v23, 1.0
	v_mov_b32_e32 v24, 1.0
	v_mov_b32_e32 v25, 1.0
	v_mov_b32_e32 v18, 1.0
	v_mov_b32_e32 v19, 1.0
	v_mov_b32_e32 v20, 1.0
	v_mov_b32_e32 v21, 1.0
	v_mov_b32_e32 v31, 0
	v_mov_b32_e32 v32, 0
	v_mov_b32_e32 v33, 0
	v_mov_b32_e32 v28, 0
	v_mov_b32_e32 v29, 0
	v_mov_b32_e32 v26, 0
	v_mov_b32_e32 v27, 0
	s_and_saveexec_b64 s[10:11], s[42:43]
	s_cbranch_execz .LBB0_268
	v_lshlrev_b64 v[18:19], 6, v[180:181]
	v_and_b32_e32 v18, 0x3fc0, v18
	v_add_u32_e32 v18, 0x21000, v18
	ds_read_b128 v[26:29], v18 offset:32
	ds_read_b128 v[34:37], v18 offset:48
	ds_read_b128 v[22:25], v18
	s_nop 0
	ds_read_b128 v[18:21], v18 offset:16
	s_waitcnt lgkmcnt(3)
	v_pk_mul_f32 v[32:33], v[172:173], v[28:29]
	v_pk_mul_f32 v[30:31], v[170:171], v[26:27]
	s_waitcnt lgkmcnt(2)
	v_pk_mul_f32 v[26:27], v[172:173], v[36:37]
	v_pk_mul_f32 v[28:29], v[170:171], v[34:35]
.LBB0_268:
	s_or_b64 exec, exec, s[10:11]
	s_waitcnt lgkmcnt(0)
	v_add_f32_e32 v34, v203, v207
	v_fmamk_f32 v34, v34, 0x3a800000, v224
	v_rsq_f32_e32 v34, v34
	s_and_b64 vcc, exec, s[8:9]
	v_pk_fma_f32 v[36:37], v[16:17], v[34:35], v[72:73] op_sel_hi:[1,0,1]
	v_pk_fma_f32 v[38:39], v[14:15], v[34:35], v[70:71] op_sel_hi:[1,0,1]
	v_pk_fma_f32 v[14:15], v[12:13], v[34:35], v[68:69] op_sel_hi:[1,0,1]
	v_pk_fma_f32 v[16:17], v[10:11], v[34:35], v[66:67] op_sel_hi:[1,0,1]
	s_cbranch_vccnz .LBB0_270
	ds_bpermute_b32 v10, v187, v38
	ds_bpermute_b32 v11, v187, v39
	ds_bpermute_b32 v12, v187, v16
	ds_bpermute_b32 v40, v187, v36
	ds_bpermute_b32 v41, v187, v37
	ds_bpermute_b32 v13, v187, v17
	ds_bpermute_b32 v42, v187, v14
	ds_bpermute_b32 v43, v187, v15
	s_waitcnt lgkmcnt(6)
	v_pk_mul_f32 v[10:11], v[30:31], v[10:11]
	s_waitcnt lgkmcnt(3)
	v_pk_mul_f32 v[40:41], v[32:33], v[40:41]
	v_pk_fma_f32 v[38:39], v[38:39], v[22:23], v[10:11]
	s_waitcnt lgkmcnt(2)
	v_pk_mul_f32 v[10:11], v[28:29], v[12:13]
	s_waitcnt lgkmcnt(0)
	v_pk_mul_f32 v[12:13], v[26:27], v[42:43]
	v_pk_fma_f32 v[36:37], v[36:37], v[24:25], v[40:41]
	v_pk_fma_f32 v[14:15], v[14:15], v[20:21], v[12:13]
	v_pk_fma_f32 v[16:17], v[16:17], v[18:19], v[10:11]
.LBB0_270:
	v_mov_b32_e32 v12, v138
	v_mov_b32_e32 v13, v138
	v_and_b32_e32 v10, 0x1fff, v180
	v_bitop3_b32 v40, v180, s44, v232 bitop3:0x80
	v_pk_mul_f32 v[36:37], v[12:13], v[36:37]
	v_lshrrev_b32_e32 v10, s19, v10
	v_pk_mul_f32 v[38:39], v[138:139], v[38:39]
	v_pk_mul_f32 v[42:43], v[12:13], v[14:15]
	v_cvt_pk_bf16_f32 v14, v38, v39
	v_cvt_pk_bf16_f32 v15, v36, v37
	v_add_u32_e32 v36, v100, v40
	v_lshlrev_b32_e32 v10, 7, v10
	v_mov_b32_e32 v11, v191
	v_ashrrev_i32_e32 v37, 31, v36
	v_lshl_add_u64 v[10:11], v[140:141], 0, v[10:11]
	v_lshlrev_b64 v[36:37], s17, v[36:37]
	v_pk_mul_f32 v[16:17], v[138:139], v[16:17]
	v_lshl_add_u64 v[36:37], v[36:37], 1, v[10:11]
	v_mov_b32_e32 v35, v34
	v_cvt_pk_bf16_f32 v16, v16, v17
	v_cvt_pk_bf16_f32 v17, v42, v43
	global_store_dwordx4 v[36:37], v[14:17], off
	v_pk_fma_f32 v[6:7], v[6:7], v[34:35], v[54:55]
	s_and_b64 vcc, exec, s[8:9]
	v_mov_b32_e32 v14, v34
	v_mov_b32_e32 v15, v34
	v_pk_fma_f32 v[8:9], v[8:9], v[14:15], v[56:57]
	v_pk_fma_f32 v[4:5], v[4:5], v[14:15], v[52:53]
	v_pk_fma_f32 v[2:3], v[2:3], v[34:35], v[50:51]
	s_cbranch_vccnz .LBB0_272
	ds_bpermute_b32 v14, v187, v6
	ds_bpermute_b32 v15, v187, v7
	ds_bpermute_b32 v16, v187, v2
	ds_bpermute_b32 v34, v187, v8
	ds_bpermute_b32 v35, v187, v9
	ds_bpermute_b32 v17, v187, v3
	ds_bpermute_b32 v36, v187, v4
	ds_bpermute_b32 v37, v187, v5
	s_waitcnt lgkmcnt(6)
	v_pk_mul_f32 v[14:15], v[30:31], v[14:15]
	s_waitcnt lgkmcnt(3)
	v_pk_mul_f32 v[30:31], v[32:33], v[34:35]
	v_pk_fma_f32 v[6:7], v[6:7], v[22:23], v[14:15]
	s_waitcnt lgkmcnt(2)
	v_pk_mul_f32 v[14:15], v[28:29], v[16:17]
	s_waitcnt lgkmcnt(0)
	v_pk_mul_f32 v[16:17], v[26:27], v[36:37]
	v_pk_fma_f32 v[8:9], v[8:9], v[24:25], v[30:31]
	v_pk_fma_f32 v[4:5], v[4:5], v[20:21], v[16:17]
	v_pk_fma_f32 v[2:3], v[2:3], v[18:19], v[14:15]
